# v43 + attention near-diagonal bias/mask path made branchless: 8 clamped table lookups in flight with counted lgkmcnt waits and v_cndmask, replacing 8 serial exec-branch blocks
# speedup vs baseline: 1.0005x; 1.0005x over previous
; __device__ __forceinline__ void attn_phase(LAS unsigned char* lds, const bf16_t* proj, bf16_t* oa, const float* lamp, const float* subg, const float* relb, const float* qg, int wg, int tid) {
;     ...
;                 if (!far) {
; #pragma unroll
;                     for (int T = 0; T < 2; ++T)
; #pragma unroll
;                         for (int r = 0; r < 4; ++r) { const int rel = qw0 + fr - (k0 + 16 * T + 4 * fq + r); const int ri = rel < 0 ? 0 : (rel > 128 ? 128 : rel);
;                             const float b0 = tb[ri], b1 = tb[132 + ri];
;                             st[0][T][r] = rel < 0 ? -INFINITY : st[0][T][r] + b0; st[1][T][r] = rel < 0 ? -INFINITY : st[1][T][r] + b1; }
;                 }
.Lat_noload:
	s_and_b64 vcc, exec, vcc
	s_cbranch_vccnz .LBB0_633
	v_add_u32_e32 v0, s36, v247
	s_movk_i32 s30, 0x80
	s_mov_b32 s31, 0x11800
	v_mov_b32_e32 v164, 0xff800000
	v_add_u32_e32 v220, 31, v0
	v_add_u32_e32 v222, 30, v0
	v_add_u32_e32 v224, 29, v0
	v_add_u32_e32 v226, 28, v0
	v_add_u32_e32 v228, 15, v0
	v_add_u32_e32 v230, 14, v0
	v_add_u32_e32 v162, 13, v0
	v_med3_i32 v220, v220, 0, s30
	v_med3_i32 v222, v222, 0, s30
	v_med3_i32 v224, v224, 0, s30
	v_med3_i32 v226, v226, 0, s30
	v_med3_i32 v228, v228, 0, s30
	v_med3_i32 v230, v230, 0, s30
	v_med3_i32 v162, v162, 0, s30
	v_lshl_add_u32 v220, v220, 2, s31
	v_lshl_add_u32 v222, v222, 2, s31
	v_lshl_add_u32 v224, v224, 2, s31
	v_lshl_add_u32 v226, v226, 2, s31
	v_lshl_add_u32 v228, v228, 2, s31
	v_lshl_add_u32 v230, v230, 2, s31
	v_lshl_add_u32 v162, v162, 2, s31
	ds_read2_b32 v[220:221], v220 offset1:132
	ds_read2_b32 v[222:223], v222 offset1:132
	ds_read2_b32 v[224:225], v224 offset1:132
	ds_read2_b32 v[226:227], v226 offset1:132
	ds_read2_b32 v[228:229], v228 offset1:132
	ds_read2_b32 v[230:231], v230 offset1:132
	ds_read2_b32 v[162:163], v162 offset1:132
	s_waitcnt lgkmcnt(6)
	v_cmp_lt_i32_e32 vcc, -32, v0
	v_add_f32_e32 v220, v146, v220
	v_add_f32_e32 v221, v158, v221
	v_cndmask_b32_e32 v146, v164, v220, vcc
	v_cndmask_b32_e32 v158, v164, v221, vcc
	v_add_u32_e32 v220, 12, v0
	v_med3_i32 v220, v220, 0, s30
	v_lshl_add_u32 v220, v220, 2, s31
	ds_read2_b32 v[220:221], v220 offset1:132
	s_waitcnt lgkmcnt(6)
	v_cmp_lt_i32_e32 vcc, -31, v0
	v_add_f32_e32 v222, v147, v222
	v_add_f32_e32 v223, v159, v223
	v_cndmask_b32_e32 v147, v164, v222, vcc
	v_cndmask_b32_e32 v159, v164, v223, vcc
	s_waitcnt lgkmcnt(5)
	v_cmp_lt_i32_e32 vcc, -30, v0
	v_add_f32_e32 v224, v148, v224
	v_add_f32_e32 v225, v160, v225
	v_cndmask_b32_e32 v148, v164, v224, vcc
	v_cndmask_b32_e32 v160, v164, v225, vcc
	s_waitcnt lgkmcnt(4)
	v_cmp_lt_i32_e32 vcc, -29, v0
	v_add_f32_e32 v226, v149, v226
	v_add_f32_e32 v227, v161, v227
	v_cndmask_b32_e32 v149, v164, v226, vcc
	v_cndmask_b32_e32 v161, v164, v227, vcc
	s_waitcnt lgkmcnt(3)
	v_cmp_lt_i32_e32 vcc, -16, v0
	v_add_f32_e32 v228, v150, v228
	v_add_f32_e32 v229, v154, v229
	v_cndmask_b32_e32 v150, v164, v228, vcc
	v_cndmask_b32_e32 v154, v164, v229, vcc
	s_waitcnt lgkmcnt(2)
	v_cmp_lt_i32_e32 vcc, -15, v0
	v_add_f32_e32 v230, v151, v230
	v_add_f32_e32 v231, v155, v231
	v_cndmask_b32_e32 v151, v164, v230, vcc
	v_cndmask_b32_e32 v155, v164, v231, vcc
	s_waitcnt lgkmcnt(1)
	v_cmp_lt_i32_e32 vcc, -14, v0
	v_add_f32_e32 v162, v152, v162
	v_add_f32_e32 v163, v156, v163
	v_cndmask_b32_e32 v152, v164, v162, vcc
	v_cndmask_b32_e32 v156, v164, v163, vcc
	s_waitcnt lgkmcnt(0)
	v_cmp_lt_i32_e32 vcc, -13, v0
	v_add_f32_e32 v220, v153, v220
	v_add_f32_e32 v221, v157, v221
	v_cndmask_b32_e32 v153, v164, v220, vcc
	v_cndmask_b32_e32 v157, v164, v221, vcc
